# lru_x weight transposes of the remaining P0 also issue two items of loads together
# speedup vs baseline: 1.0022x; 1.0022x over previous
.LBB0_173:
	s_andn2_b64 vcc, exec, s[2:3]
	s_cbranch_vccnz .LBB0_154
	s_add_i32 s36, s31, s78
	s_cmp_gt_u32 s36, 0xfff
	s_cbranch_scc1 .Lk_XR_single
	s_ashr_i32 s0, s31, 31
	s_lshr_b32 s0, s0, 26
	s_add_i32 s0, s31, s0
	s_and_b32 s2, s0, 0xffffffc0
	s_ashr_i32 s3, s0, 6
	s_sub_i32 s0, s31, s2
	v_readlane_b32 s40, v254, 19
	s_add_i32 s4, s0, 0xc0
	s_mul_i32 s5, s3, 0x280000
	v_readlane_b32 s48, v254, 27
	s_mul_hi_i32 s0, s3, 0x280000
	v_readlane_b32 s49, v254, 28
	s_add_u32 s5, s48, s5
	s_addc_u32 s33, s49, s0
	s_lshl_b32 s0, s3, 11
	s_sub_i32 s0, s16, s0
	s_addk_i32 s0, 0x1800
	s_lshl_b64 s[34:35], s[0:1], 2
	s_add_u32 s34, s5, s34
	s_addc_u32 s35, s33, s35
	v_lshl_add_u64 v[98:99], s[34:35], 0, v[142:143]
	v_mov_b32_e32 v67, v143
	v_lshl_add_u64 v[94:95], v[98:99], 0, v[66:67]
	v_add_co_u32_e32 v90, vcc, s30, v94
	v_lshl_add_u64 v[70:71], v[98:99], 0, v[38:39]
	v_lshl_add_u64 v[74:75], v[98:99], 0, v[40:41]
	v_lshl_add_u64 v[78:79], v[98:99], 0, v[42:43]
	v_lshl_add_u64 v[82:83], v[98:99], 0, v[44:45]
	v_addc_co_u32_e32 v91, vcc, 0, v95, vcc
	global_load_dwordx4 v[70:73], v[70:71], off
	s_nop 0
	global_load_dwordx4 v[74:77], v[74:75], off
	s_nop 0
	global_load_dwordx4 v[78:81], v[78:79], off
	s_nop 0
	global_load_dwordx4 v[82:85], v[82:83], off
	s_nop 0
	global_load_dwordx4 v[86:89], v[94:95], off
	s_nop 0
	global_load_dwordx4 v[90:93], v[90:91], off
	v_add_co_u32_e32 v94, vcc, s26, v94
	v_mov_b32_e32 v69, v143
	s_nop 0
	v_addc_co_u32_e32 v95, vcc, 0, v95, vcc
	global_load_dwordx4 v[94:97], v[94:95], off
	v_lshl_add_u64 v[98:99], v[98:99], 0, v[68:69]
	global_load_dwordx4 v[98:101], v[98:99], off
	s_add_i32 s31, s31, s78
	s_add_i32 s16, s16, s37
	s_add_i32 s17, s17, s18
	s_mov_b32 s69, 0
	s_ashr_i32 s68, s31, 31
	s_lshr_b32 s68, s68, 26
	s_add_i32 s68, s31, s68
	s_and_b32 s70, s68, 0xffffffc0
	s_ashr_i32 s71, s68, 6
	s_sub_i32 s68, s31, s70
	v_readlane_b32 s82, v254, 19
	s_add_i32 s72, s68, 0xc0
	s_mul_i32 s73, s71, 0x280000
	v_readlane_b32 s92, v254, 27
	s_mul_hi_i32 s68, s71, 0x280000
	v_readlane_b32 s93, v254, 28
	s_add_u32 s73, s92, s73
	s_addc_u32 s79, s93, s68
	s_lshl_b32 s68, s71, 11
	s_sub_i32 s68, s16, s68
	s_addk_i32 s68, 0x1800
	s_lshl_b64 s[74:75], s[68:69], 2
	s_add_u32 s74, s73, s74
	s_addc_u32 s75, s79, s75
	v_lshl_add_u64 v[248:249], s[74:75], 0, v[142:143]
	v_mov_b32_e32 v67, v143
	v_lshl_add_u64 v[244:245], v[248:249], 0, v[66:67]
	v_add_co_u32_e32 v240, vcc, s30, v244
	v_lshl_add_u64 v[220:221], v[248:249], 0, v[38:39]
	v_lshl_add_u64 v[224:225], v[248:249], 0, v[40:41]
	v_lshl_add_u64 v[228:229], v[248:249], 0, v[42:43]
	v_lshl_add_u64 v[232:233], v[248:249], 0, v[44:45]
	v_addc_co_u32_e32 v241, vcc, 0, v245, vcc
	global_load_dwordx4 v[220:223], v[220:221], off
	s_nop 0
	global_load_dwordx4 v[224:227], v[224:225], off
	s_nop 0
	global_load_dwordx4 v[228:231], v[228:229], off
	s_nop 0
	global_load_dwordx4 v[232:235], v[232:233], off
	s_nop 0
	global_load_dwordx4 v[236:239], v[244:245], off
	s_nop 0
	global_load_dwordx4 v[240:243], v[240:241], off
	v_add_co_u32_e32 v244, vcc, s26, v244
	v_mov_b32_e32 v69, v143
	s_nop 0
	v_addc_co_u32_e32 v245, vcc, 0, v245, vcc
	global_load_dwordx4 v[244:247], v[244:245], off
	v_lshl_add_u64 v[248:249], v[248:249], 0, v[68:69]
	global_load_dwordx4 v[248:251], v[248:249], off
	s_sub_i32 s31, s31, s78
	s_sub_i32 s16, s16, s37
	s_sub_i32 s17, s17, s18
	v_add_u32_e32 v11, 0x420, v173
	v_add_u32_e32 v13, 0x428, v173
	v_add_u32_e32 v15, 0x840, v173
	v_add_u32_e32 v33, 0x848, v173
	v_add_u32_e32 v47, 0xc60, v173
	v_add_u32_e32 v49, 0xc68, v173
	v_add_u32_e32 v51, 0x1080, v173
	v_add_u32_e32 v53, 0x1088, v173
	v_add_u32_e32 v55, 0x14a0, v173
	v_add_u32_e32 v57, 0x14a8, v173
	v_add_u32_e32 v59, 0x18c0, v173
	v_add_u32_e32 v61, 0x18c8, v173
	v_add_u32_e32 v63, 0x1ce0, v173
	v_add_u32_e32 v65, 0x1ce8, v173
	s_mov_b32 s5, s1
	s_lshl_b64 s[4:5], s[4:5], 18
	s_add_u32 s0, s10, s4
	s_addc_u32 s4, s11, s5
	s_ashr_i32 s3, s2, 31
	s_lshl_b64 s[2:3], s[2:3], 1
	s_add_u32 s2, s0, s2
	v_lshlrev_b32_e32 v102, 1, v12
	v_mov_b32_e32 v103, v143
	s_addc_u32 s3, s4, s3
	v_lshlrev_b32_e32 v104, 1, v14
	v_mov_b32_e32 v105, v143
	v_lshl_add_u64 v[102:103], s[2:3], 0, v[102:103]
	v_lshl_add_u64 v[102:103], v[102:103], 0, v[104:105]
	v_readlane_b32 s41, v254, 20
	v_readlane_b32 s42, v254, 21
	v_readlane_b32 s43, v254, 22
	v_readlane_b32 s44, v254, 23
	v_readlane_b32 s45, v254, 24
	v_readlane_b32 s46, v254, 25
	v_readlane_b32 s47, v254, 26
	v_readlane_b32 s50, v254, 29
	v_readlane_b32 s51, v254, 30
	v_readlane_b32 s52, v254, 31
	v_readlane_b32 s53, v254, 32
	v_readlane_b32 s54, v254, 33
	v_readlane_b32 s55, v254, 34
	s_waitcnt vmcnt(15)
	ds_write2_b32 v173, v70, v71 offset1:1
	ds_write2_b32 v173, v72, v73 offset0:2 offset1:3
	s_waitcnt vmcnt(14)
	ds_write2_b32 v11, v74, v75 offset1:1
	ds_write2_b32 v13, v76, v77 offset1:1
	s_waitcnt vmcnt(13)
	ds_write2_b32 v15, v78, v79 offset1:1
	ds_write2_b32 v33, v80, v81 offset1:1
	s_waitcnt vmcnt(12)
	ds_write2_b32 v47, v82, v83 offset1:1
	ds_write2_b32 v49, v84, v85 offset1:1
	s_waitcnt vmcnt(11)
	ds_write2_b32 v51, v86, v87 offset1:1
	ds_write2_b32 v53, v88, v89 offset1:1
	s_waitcnt vmcnt(10)
	ds_write2_b32 v55, v90, v91 offset1:1
	ds_write2_b32 v57, v92, v93 offset1:1
	s_waitcnt vmcnt(9)
	ds_write2_b32 v59, v94, v95 offset1:1
	ds_write2_b32 v61, v96, v97 offset1:1
	s_waitcnt vmcnt(8)
	ds_write2_b32 v63, v98, v99 offset1:1
	ds_write2_b32 v65, v100, v101 offset1:1
	s_waitcnt lgkmcnt(0)
	ds_read2_b32 v[74:75], v7 offset0:33 offset1:41
	ds_read2_b32 v[76:77], v7 offset1:8
	ds_read2_b32 v[78:79], v7 offset0:66 offset1:74
	ds_read2_b32 v[80:81], v7 offset0:99 offset1:107
	ds_read2_b32 v[82:83], v7 offset0:132 offset1:140
	ds_read2_b32 v[84:85], v7 offset0:165 offset1:173
	s_waitcnt lgkmcnt(4)
	v_bfe_u32 v11, v76, 16, 1
	ds_read2_b32 v[86:87], v7 offset0:198 offset1:206
	v_bfe_u32 v13, v74, 16, 1
	v_add3_u32 v11, v76, v11, s19
	ds_read2_b32 v[88:89], v7 offset0:231 offset1:239
	s_waitcnt lgkmcnt(3)
	v_bfe_u32 v47, v82, 16, 1
	v_add3_u32 v13, v74, v13, s19
	v_lshrrev_b32_e32 v11, 16, v11
	v_add3_u32 v47, v82, v47, s19
	v_and_or_b32 v70, v13, s20, v11
	s_waitcnt lgkmcnt(2)
	v_bfe_u32 v13, v84, 16, 1
	v_lshrrev_b32_e32 v11, 16, v47
	v_add3_u32 v13, v84, v13, s19
	v_and_or_b32 v72, v13, s20, v11
	s_waitcnt lgkmcnt(1)
	v_bfe_u32 v11, v86, 16, 1
	v_add3_u32 v11, v86, v11, s19
	s_waitcnt lgkmcnt(0)
	v_bfe_u32 v13, v88, 16, 1
	v_bfe_u32 v15, v78, 16, 1
	v_lshrrev_b32_e32 v11, 16, v11
	v_add3_u32 v13, v88, v13, s19
	v_bfe_u32 v33, v80, 16, 1
	v_add3_u32 v15, v78, v15, s19
	v_and_or_b32 v73, v13, s20, v11
	v_bfe_u32 v11, v77, 16, 1
	v_add3_u32 v33, v80, v33, s19
	v_lshrrev_b32_e32 v15, 16, v15
	v_add3_u32 v11, v77, v11, s19
	v_bfe_u32 v13, v75, 16, 1
	v_and_or_b32 v71, v33, s20, v15
	v_lshl_add_u64 v[90:91], v[102:103], 0, v[16:17]
	v_lshrrev_b32_e32 v11, 16, v11
	v_add3_u32 v13, v75, v13, s19
	global_store_dwordx4 v[90:91], v[70:73], off
	ds_read2_b32 v[74:75], v7 offset0:16 offset1:24
	v_lshl_add_u64 v[76:77], v[102:103], 0, v[18:19]
	v_and_or_b32 v70, v13, s20, v11
	v_bfe_u32 v11, v79, 16, 1
	v_add3_u32 v11, v79, v11, s19
	v_bfe_u32 v13, v81, 16, 1
	v_lshrrev_b32_e32 v11, 16, v11
	v_add3_u32 v13, v81, v13, s19
	v_and_or_b32 v71, v13, s20, v11
	v_bfe_u32 v11, v83, 16, 1
	v_add3_u32 v11, v83, v11, s19
	v_bfe_u32 v13, v85, 16, 1
	v_lshrrev_b32_e32 v11, 16, v11
	v_add3_u32 v13, v85, v13, s19
	v_and_or_b32 v72, v13, s20, v11
	v_bfe_u32 v11, v87, 16, 1
	v_add3_u32 v11, v87, v11, s19
	v_bfe_u32 v13, v89, 16, 1
	v_lshrrev_b32_e32 v11, 16, v11
	v_add3_u32 v13, v89, v13, s19
	v_and_or_b32 v73, v13, s20, v11
	global_store_dwordx4 v[76:77], v[70:73], off
	ds_read2_b32 v[76:77], v7 offset0:49 offset1:57
	ds_read2_b32 v[78:79], v7 offset0:82 offset1:90
	ds_read2_b32 v[80:81], v7 offset0:115 offset1:123
	s_waitcnt lgkmcnt(3)
	v_bfe_u32 v11, v74, 16, 1
	v_add3_u32 v11, v74, v11, s19
	s_waitcnt lgkmcnt(2)
	v_bfe_u32 v13, v76, 16, 1
	ds_read2_b32 v[82:83], v7 offset0:148 offset1:156
	v_lshrrev_b32_e32 v11, 16, v11
	v_add3_u32 v13, v76, v13, s19
	ds_read2_b32 v[84:85], v7 offset0:181 offset1:189
	v_and_or_b32 v70, v13, s20, v11
	s_waitcnt lgkmcnt(3)
	v_bfe_u32 v11, v78, 16, 1
	v_add3_u32 v11, v78, v11, s19
	s_waitcnt lgkmcnt(2)
	v_bfe_u32 v13, v80, 16, 1
	ds_read2_b32 v[86:87], v7 offset0:214 offset1:222
	v_lshrrev_b32_e32 v11, 16, v11
	v_add3_u32 v13, v80, v13, s19
	ds_read2_b32 v[88:89], v7 offset0:247 offset1:255
	v_and_or_b32 v71, v13, s20, v11
	s_waitcnt lgkmcnt(3)
	v_bfe_u32 v11, v82, 16, 1
	v_add3_u32 v11, v82, v11, s19
	s_waitcnt lgkmcnt(2)
	v_bfe_u32 v13, v84, 16, 1
	v_lshrrev_b32_e32 v11, 16, v11
	v_add3_u32 v13, v84, v13, s19
	v_and_or_b32 v72, v13, s20, v11
	s_waitcnt lgkmcnt(1)
	v_bfe_u32 v11, v86, 16, 1
	v_add3_u32 v11, v86, v11, s19
	s_waitcnt lgkmcnt(0)
	v_bfe_u32 v13, v88, 16, 1
	v_lshrrev_b32_e32 v11, 16, v11
	v_add3_u32 v13, v88, v13, s19
	v_and_or_b32 v73, v13, s20, v11
	v_bfe_u32 v11, v75, 16, 1
	v_add3_u32 v11, v75, v11, s19
	v_bfe_u32 v13, v77, 16, 1
	v_lshl_add_u64 v[90:91], v[102:103], 0, v[20:21]
	v_lshrrev_b32_e32 v11, 16, v11
	v_add3_u32 v13, v77, v13, s19
	global_store_dwordx4 v[90:91], v[70:73], off
	v_lshl_add_u64 v[74:75], v[102:103], 0, v[22:23]
	s_nop 0
	v_and_or_b32 v70, v13, s20, v11
	v_bfe_u32 v11, v79, 16, 1
	v_add3_u32 v11, v79, v11, s19
	v_bfe_u32 v13, v81, 16, 1
	v_lshrrev_b32_e32 v11, 16, v11
	v_add3_u32 v13, v81, v13, s19
	v_and_or_b32 v71, v13, s20, v11
	v_bfe_u32 v11, v83, 16, 1
	v_add3_u32 v11, v83, v11, s19
	v_bfe_u32 v13, v85, 16, 1
	v_lshrrev_b32_e32 v11, 16, v11
	v_add3_u32 v13, v85, v13, s19
	v_and_or_b32 v72, v13, s20, v11
	v_bfe_u32 v11, v87, 16, 1
	v_add3_u32 v11, v87, v11, s19
	v_bfe_u32 v13, v89, 16, 1
	v_lshrrev_b32_e32 v11, 16, v11
	v_add3_u32 v13, v89, v13, s19
	v_and_or_b32 v73, v13, s20, v11
	global_store_dwordx4 v[74:75], v[70:73], off
	s_waitcnt lgkmcnt(0)
	s_add_i32 s31, s31, s78
	s_add_i32 s16, s16, s37
	s_add_i32 s17, s17, s18
	s_ashr_i32 s0, s31, 31
	s_lshr_b32 s0, s0, 26
	s_add_i32 s0, s31, s0
	s_and_b32 s2, s0, 0xffffffc0
	s_ashr_i32 s3, s0, 6
	s_sub_i32 s0, s31, s2
	v_readlane_b32 s40, v254, 19
	s_add_i32 s4, s0, 0xc0
	s_mul_i32 s5, s3, 0x280000
	v_readlane_b32 s48, v254, 27
	s_mul_hi_i32 s0, s3, 0x280000
	v_readlane_b32 s49, v254, 28
	s_add_u32 s5, s48, s5
	s_addc_u32 s33, s49, s0
	s_lshl_b32 s0, s3, 11
	s_sub_i32 s0, s16, s0
	s_addk_i32 s0, 0x1800
	s_lshl_b64 s[34:35], s[0:1], 2
	s_add_u32 s34, s5, s34
	s_addc_u32 s35, s33, s35
	v_lshl_add_u64 v[98:99], s[34:35], 0, v[142:143]
	v_mov_b32_e32 v67, v143
	v_lshl_add_u64 v[94:95], v[98:99], 0, v[66:67]
	v_add_co_u32_e32 v90, vcc, s30, v94
	v_lshl_add_u64 v[70:71], v[98:99], 0, v[38:39]
	v_lshl_add_u64 v[74:75], v[98:99], 0, v[40:41]
	v_lshl_add_u64 v[78:79], v[98:99], 0, v[42:43]
	v_lshl_add_u64 v[82:83], v[98:99], 0, v[44:45]
	v_addc_co_u32_e32 v91, vcc, 0, v95, vcc
	s_nop 0
	s_nop 0
	s_nop 0
	s_nop 0
	s_nop 0
	v_add_co_u32_e32 v94, vcc, s26, v94
	v_mov_b32_e32 v69, v143
	s_nop 0
	v_addc_co_u32_e32 v95, vcc, 0, v95, vcc
	v_lshl_add_u64 v[98:99], v[98:99], 0, v[68:69]
	v_add_u32_e32 v11, 0x420, v173
	v_add_u32_e32 v13, 0x428, v173
	v_add_u32_e32 v15, 0x840, v173
	v_add_u32_e32 v33, 0x848, v173
	v_add_u32_e32 v47, 0xc60, v173
	v_add_u32_e32 v49, 0xc68, v173
	v_add_u32_e32 v51, 0x1080, v173
	v_add_u32_e32 v53, 0x1088, v173
	v_add_u32_e32 v55, 0x14a0, v173
	v_add_u32_e32 v57, 0x14a8, v173
	v_add_u32_e32 v59, 0x18c0, v173
	v_add_u32_e32 v61, 0x18c8, v173
	v_add_u32_e32 v63, 0x1ce0, v173
	v_add_u32_e32 v65, 0x1ce8, v173
	s_mov_b32 s5, s1
	s_lshl_b64 s[4:5], s[4:5], 18
	s_add_u32 s0, s10, s4
	s_addc_u32 s4, s11, s5
	s_ashr_i32 s3, s2, 31
	s_lshl_b64 s[2:3], s[2:3], 1
	s_add_u32 s2, s0, s2
	v_lshlrev_b32_e32 v102, 1, v12
	v_mov_b32_e32 v103, v143
	s_addc_u32 s3, s4, s3
	v_lshlrev_b32_e32 v104, 1, v14
	v_mov_b32_e32 v105, v143
	v_lshl_add_u64 v[102:103], s[2:3], 0, v[102:103]
	v_lshl_add_u64 v[102:103], v[102:103], 0, v[104:105]
	v_readlane_b32 s41, v254, 20
	v_readlane_b32 s42, v254, 21
	v_readlane_b32 s43, v254, 22
	v_readlane_b32 s44, v254, 23
	v_readlane_b32 s45, v254, 24
	v_readlane_b32 s46, v254, 25
	v_readlane_b32 s47, v254, 26
	v_readlane_b32 s50, v254, 29
	v_readlane_b32 s51, v254, 30
	v_readlane_b32 s52, v254, 31
	v_readlane_b32 s53, v254, 32
	v_readlane_b32 s54, v254, 33
	v_readlane_b32 s55, v254, 34
	s_waitcnt vmcnt(11)
	ds_write2_b32 v173, v220, v221 offset1:1
	ds_write2_b32 v173, v222, v223 offset0:2 offset1:3
	s_waitcnt vmcnt(10)
	ds_write2_b32 v11, v224, v225 offset1:1
	ds_write2_b32 v13, v226, v227 offset1:1
	s_waitcnt vmcnt(9)
	ds_write2_b32 v15, v228, v229 offset1:1
	ds_write2_b32 v33, v230, v231 offset1:1
	s_waitcnt vmcnt(8)
	ds_write2_b32 v47, v232, v233 offset1:1
	ds_write2_b32 v49, v234, v235 offset1:1
	s_waitcnt vmcnt(7)
	ds_write2_b32 v51, v236, v237 offset1:1
	ds_write2_b32 v53, v238, v239 offset1:1
	s_waitcnt vmcnt(6)
	ds_write2_b32 v55, v240, v241 offset1:1
	ds_write2_b32 v57, v242, v243 offset1:1
	s_waitcnt vmcnt(5)
	ds_write2_b32 v59, v244, v245 offset1:1
	ds_write2_b32 v61, v246, v247 offset1:1
	s_waitcnt vmcnt(4)
	ds_write2_b32 v63, v248, v249 offset1:1
	ds_write2_b32 v65, v250, v251 offset1:1
	s_waitcnt lgkmcnt(0)
	ds_read2_b32 v[74:75], v7 offset0:33 offset1:41
	ds_read2_b32 v[76:77], v7 offset1:8
	ds_read2_b32 v[78:79], v7 offset0:66 offset1:74
	ds_read2_b32 v[80:81], v7 offset0:99 offset1:107
	ds_read2_b32 v[82:83], v7 offset0:132 offset1:140
	ds_read2_b32 v[84:85], v7 offset0:165 offset1:173
	s_waitcnt lgkmcnt(4)
	v_bfe_u32 v11, v76, 16, 1
	ds_read2_b32 v[86:87], v7 offset0:198 offset1:206
	v_bfe_u32 v13, v74, 16, 1
	v_add3_u32 v11, v76, v11, s19
	ds_read2_b32 v[88:89], v7 offset0:231 offset1:239
	s_waitcnt lgkmcnt(3)
	v_bfe_u32 v47, v82, 16, 1
	v_add3_u32 v13, v74, v13, s19
	v_lshrrev_b32_e32 v11, 16, v11
	v_add3_u32 v47, v82, v47, s19
	v_and_or_b32 v70, v13, s20, v11
	s_waitcnt lgkmcnt(2)
	v_bfe_u32 v13, v84, 16, 1
	v_lshrrev_b32_e32 v11, 16, v47
	v_add3_u32 v13, v84, v13, s19
	v_and_or_b32 v72, v13, s20, v11
	s_waitcnt lgkmcnt(1)
	v_bfe_u32 v11, v86, 16, 1
	v_add3_u32 v11, v86, v11, s19
	s_waitcnt lgkmcnt(0)
	v_bfe_u32 v13, v88, 16, 1
	v_bfe_u32 v15, v78, 16, 1
	v_lshrrev_b32_e32 v11, 16, v11
	v_add3_u32 v13, v88, v13, s19
	v_bfe_u32 v33, v80, 16, 1
	v_add3_u32 v15, v78, v15, s19
	v_and_or_b32 v73, v13, s20, v11
	v_bfe_u32 v11, v77, 16, 1
	v_add3_u32 v33, v80, v33, s19
	v_lshrrev_b32_e32 v15, 16, v15
	v_add3_u32 v11, v77, v11, s19
	v_bfe_u32 v13, v75, 16, 1
	v_and_or_b32 v71, v33, s20, v15
	v_lshl_add_u64 v[90:91], v[102:103], 0, v[16:17]
	v_lshrrev_b32_e32 v11, 16, v11
	v_add3_u32 v13, v75, v13, s19
	global_store_dwordx4 v[90:91], v[70:73], off
	ds_read2_b32 v[74:75], v7 offset0:16 offset1:24
	v_lshl_add_u64 v[76:77], v[102:103], 0, v[18:19]
	v_and_or_b32 v70, v13, s20, v11
	v_bfe_u32 v11, v79, 16, 1
	v_add3_u32 v11, v79, v11, s19
	v_bfe_u32 v13, v81, 16, 1
	v_lshrrev_b32_e32 v11, 16, v11
	v_add3_u32 v13, v81, v13, s19
	v_and_or_b32 v71, v13, s20, v11
	v_bfe_u32 v11, v83, 16, 1
	v_add3_u32 v11, v83, v11, s19
	v_bfe_u32 v13, v85, 16, 1
	v_lshrrev_b32_e32 v11, 16, v11
	v_add3_u32 v13, v85, v13, s19
	v_and_or_b32 v72, v13, s20, v11
	v_bfe_u32 v11, v87, 16, 1
	v_add3_u32 v11, v87, v11, s19
	v_bfe_u32 v13, v89, 16, 1
	v_lshrrev_b32_e32 v11, 16, v11
	v_add3_u32 v13, v89, v13, s19
	v_and_or_b32 v73, v13, s20, v11
	global_store_dwordx4 v[76:77], v[70:73], off
	ds_read2_b32 v[76:77], v7 offset0:49 offset1:57
	ds_read2_b32 v[78:79], v7 offset0:82 offset1:90
	ds_read2_b32 v[80:81], v7 offset0:115 offset1:123
	s_waitcnt lgkmcnt(3)
	v_bfe_u32 v11, v74, 16, 1
	v_add3_u32 v11, v74, v11, s19
	s_waitcnt lgkmcnt(2)
	v_bfe_u32 v13, v76, 16, 1
	ds_read2_b32 v[82:83], v7 offset0:148 offset1:156
	v_lshrrev_b32_e32 v11, 16, v11
	v_add3_u32 v13, v76, v13, s19
	ds_read2_b32 v[84:85], v7 offset0:181 offset1:189
	v_and_or_b32 v70, v13, s20, v11
	s_waitcnt lgkmcnt(3)
	v_bfe_u32 v11, v78, 16, 1
	v_add3_u32 v11, v78, v11, s19
	s_waitcnt lgkmcnt(2)
	v_bfe_u32 v13, v80, 16, 1
	ds_read2_b32 v[86:87], v7 offset0:214 offset1:222
	v_lshrrev_b32_e32 v11, 16, v11
	v_add3_u32 v13, v80, v13, s19
	ds_read2_b32 v[88:89], v7 offset0:247 offset1:255
	v_and_or_b32 v71, v13, s20, v11
	s_waitcnt lgkmcnt(3)
	v_bfe_u32 v11, v82, 16, 1
	v_add3_u32 v11, v82, v11, s19
	s_waitcnt lgkmcnt(2)
	v_bfe_u32 v13, v84, 16, 1
	v_lshrrev_b32_e32 v11, 16, v11
	v_add3_u32 v13, v84, v13, s19
	v_and_or_b32 v72, v13, s20, v11
	s_waitcnt lgkmcnt(1)
	v_bfe_u32 v11, v86, 16, 1
	v_add3_u32 v11, v86, v11, s19
	s_waitcnt lgkmcnt(0)
	v_bfe_u32 v13, v88, 16, 1
	v_lshrrev_b32_e32 v11, 16, v11
	v_add3_u32 v13, v88, v13, s19
	v_and_or_b32 v73, v13, s20, v11
	v_bfe_u32 v11, v75, 16, 1
	v_add3_u32 v11, v75, v11, s19
	v_bfe_u32 v13, v77, 16, 1
	v_lshl_add_u64 v[90:91], v[102:103], 0, v[20:21]
	v_lshrrev_b32_e32 v11, 16, v11
	v_add3_u32 v13, v77, v13, s19
	global_store_dwordx4 v[90:91], v[70:73], off
	v_lshl_add_u64 v[74:75], v[102:103], 0, v[22:23]
	s_nop 0
	v_and_or_b32 v70, v13, s20, v11
	v_bfe_u32 v11, v79, 16, 1
	v_add3_u32 v11, v79, v11, s19
	v_bfe_u32 v13, v81, 16, 1
	v_lshrrev_b32_e32 v11, 16, v11
	v_add3_u32 v13, v81, v13, s19
	v_and_or_b32 v71, v13, s20, v11
	v_bfe_u32 v11, v83, 16, 1
	v_add3_u32 v11, v83, v11, s19
	v_bfe_u32 v13, v85, 16, 1
	v_lshrrev_b32_e32 v11, 16, v11
	v_add3_u32 v13, v85, v13, s19
	v_and_or_b32 v72, v13, s20, v11
	v_bfe_u32 v11, v87, 16, 1
	v_add3_u32 v11, v87, v11, s19
	v_bfe_u32 v13, v89, 16, 1
	v_lshrrev_b32_e32 v11, 16, v11
	v_add3_u32 v13, v89, v13, s19
	v_and_or_b32 v73, v13, s20, v11
	global_store_dwordx4 v[74:75], v[70:73], off
	s_waitcnt lgkmcnt(0)
	s_branch .LBB0_154
.Lk_XR_single:
	s_ashr_i32 s0, s31, 31
	s_lshr_b32 s0, s0, 26
	s_add_i32 s0, s31, s0
	s_and_b32 s2, s0, 0xffffffc0
	s_ashr_i32 s3, s0, 6
	s_sub_i32 s0, s31, s2
	v_readlane_b32 s40, v254, 19
	s_add_i32 s4, s0, 0xc0
	s_mul_i32 s5, s3, 0x280000
	v_readlane_b32 s48, v254, 27
	s_mul_hi_i32 s0, s3, 0x280000
	v_readlane_b32 s49, v254, 28
	s_add_u32 s5, s48, s5
	s_addc_u32 s33, s49, s0
	s_lshl_b32 s0, s3, 11
	s_sub_i32 s0, s16, s0
	s_addk_i32 s0, 0x1800
	s_lshl_b64 s[34:35], s[0:1], 2
	s_add_u32 s34, s5, s34
	s_addc_u32 s35, s33, s35
	v_lshl_add_u64 v[98:99], s[34:35], 0, v[142:143]
	v_mov_b32_e32 v67, v143
	v_lshl_add_u64 v[94:95], v[98:99], 0, v[66:67]
	v_add_co_u32_e32 v90, vcc, s30, v94
	v_lshl_add_u64 v[70:71], v[98:99], 0, v[38:39]
	v_lshl_add_u64 v[74:75], v[98:99], 0, v[40:41]
	v_lshl_add_u64 v[78:79], v[98:99], 0, v[42:43]
	v_lshl_add_u64 v[82:83], v[98:99], 0, v[44:45]
	v_addc_co_u32_e32 v91, vcc, 0, v95, vcc
	global_load_dwordx4 v[70:73], v[70:71], off
	s_nop 0
	global_load_dwordx4 v[74:77], v[74:75], off
	s_nop 0
	global_load_dwordx4 v[78:81], v[78:79], off
	s_nop 0
	global_load_dwordx4 v[82:85], v[82:83], off
	s_nop 0
	global_load_dwordx4 v[86:89], v[94:95], off
	s_nop 0
	global_load_dwordx4 v[90:93], v[90:91], off
	v_add_co_u32_e32 v94, vcc, s26, v94
	v_mov_b32_e32 v69, v143
	s_nop 0
	v_addc_co_u32_e32 v95, vcc, 0, v95, vcc
	global_load_dwordx4 v[94:97], v[94:95], off
	v_lshl_add_u64 v[98:99], v[98:99], 0, v[68:69]
	global_load_dwordx4 v[98:101], v[98:99], off
	v_add_u32_e32 v11, 0x420, v173
	v_add_u32_e32 v13, 0x428, v173
	v_add_u32_e32 v15, 0x840, v173
	v_add_u32_e32 v33, 0x848, v173
	v_add_u32_e32 v47, 0xc60, v173
	v_add_u32_e32 v49, 0xc68, v173
	v_add_u32_e32 v51, 0x1080, v173
	v_add_u32_e32 v53, 0x1088, v173
	v_add_u32_e32 v55, 0x14a0, v173
	v_add_u32_e32 v57, 0x14a8, v173
	v_add_u32_e32 v59, 0x18c0, v173
	v_add_u32_e32 v61, 0x18c8, v173
	v_add_u32_e32 v63, 0x1ce0, v173
	v_add_u32_e32 v65, 0x1ce8, v173
	s_mov_b32 s5, s1
	s_lshl_b64 s[4:5], s[4:5], 18
	s_add_u32 s0, s10, s4
	s_addc_u32 s4, s11, s5
	s_ashr_i32 s3, s2, 31
	s_lshl_b64 s[2:3], s[2:3], 1
	s_add_u32 s2, s0, s2
	v_lshlrev_b32_e32 v102, 1, v12
	v_mov_b32_e32 v103, v143
	s_addc_u32 s3, s4, s3
	v_lshlrev_b32_e32 v104, 1, v14
	v_mov_b32_e32 v105, v143
	v_lshl_add_u64 v[102:103], s[2:3], 0, v[102:103]
	v_lshl_add_u64 v[102:103], v[102:103], 0, v[104:105]
	v_readlane_b32 s41, v254, 20
	v_readlane_b32 s42, v254, 21
	v_readlane_b32 s43, v254, 22
	v_readlane_b32 s44, v254, 23
	v_readlane_b32 s45, v254, 24
	v_readlane_b32 s46, v254, 25
	v_readlane_b32 s47, v254, 26
	v_readlane_b32 s50, v254, 29
	v_readlane_b32 s51, v254, 30
	v_readlane_b32 s52, v254, 31
	v_readlane_b32 s53, v254, 32
	v_readlane_b32 s54, v254, 33
	v_readlane_b32 s55, v254, 34
	s_waitcnt vmcnt(7)
	ds_write2_b32 v173, v70, v71 offset1:1
	ds_write2_b32 v173, v72, v73 offset0:2 offset1:3
	s_waitcnt vmcnt(6)
	ds_write2_b32 v11, v74, v75 offset1:1
	ds_write2_b32 v13, v76, v77 offset1:1
	s_waitcnt vmcnt(5)
	ds_write2_b32 v15, v78, v79 offset1:1
	ds_write2_b32 v33, v80, v81 offset1:1
	s_waitcnt vmcnt(4)
	ds_write2_b32 v47, v82, v83 offset1:1
	ds_write2_b32 v49, v84, v85 offset1:1
	s_waitcnt vmcnt(3)
	ds_write2_b32 v51, v86, v87 offset1:1
	ds_write2_b32 v53, v88, v89 offset1:1
	s_waitcnt vmcnt(2)
	ds_write2_b32 v55, v90, v91 offset1:1
	ds_write2_b32 v57, v92, v93 offset1:1
	s_waitcnt vmcnt(1)
	ds_write2_b32 v59, v94, v95 offset1:1
	ds_write2_b32 v61, v96, v97 offset1:1
	s_waitcnt vmcnt(0)
	ds_write2_b32 v63, v98, v99 offset1:1
	ds_write2_b32 v65, v100, v101 offset1:1
	s_waitcnt lgkmcnt(0)
	ds_read2_b32 v[74:75], v7 offset0:33 offset1:41
	ds_read2_b32 v[76:77], v7 offset1:8
	ds_read2_b32 v[78:79], v7 offset0:66 offset1:74
	ds_read2_b32 v[80:81], v7 offset0:99 offset1:107
	ds_read2_b32 v[82:83], v7 offset0:132 offset1:140
	ds_read2_b32 v[84:85], v7 offset0:165 offset1:173
	s_waitcnt lgkmcnt(4)
	v_bfe_u32 v11, v76, 16, 1
	ds_read2_b32 v[86:87], v7 offset0:198 offset1:206
	v_bfe_u32 v13, v74, 16, 1
	v_add3_u32 v11, v76, v11, s19
	ds_read2_b32 v[88:89], v7 offset0:231 offset1:239
	s_waitcnt lgkmcnt(3)
	v_bfe_u32 v47, v82, 16, 1
	v_add3_u32 v13, v74, v13, s19
	v_lshrrev_b32_e32 v11, 16, v11
	v_add3_u32 v47, v82, v47, s19
	v_and_or_b32 v70, v13, s20, v11
	s_waitcnt lgkmcnt(2)
	v_bfe_u32 v13, v84, 16, 1
	v_lshrrev_b32_e32 v11, 16, v47
	v_add3_u32 v13, v84, v13, s19
	v_and_or_b32 v72, v13, s20, v11
	s_waitcnt lgkmcnt(1)
	v_bfe_u32 v11, v86, 16, 1
	v_add3_u32 v11, v86, v11, s19
	s_waitcnt lgkmcnt(0)
	v_bfe_u32 v13, v88, 16, 1
	v_bfe_u32 v15, v78, 16, 1
	v_lshrrev_b32_e32 v11, 16, v11
	v_add3_u32 v13, v88, v13, s19
	v_bfe_u32 v33, v80, 16, 1
	v_add3_u32 v15, v78, v15, s19
	v_and_or_b32 v73, v13, s20, v11
	v_bfe_u32 v11, v77, 16, 1
	v_add3_u32 v33, v80, v33, s19
	v_lshrrev_b32_e32 v15, 16, v15
	v_add3_u32 v11, v77, v11, s19
	v_bfe_u32 v13, v75, 16, 1
	v_and_or_b32 v71, v33, s20, v15
	v_lshl_add_u64 v[90:91], v[102:103], 0, v[16:17]
	v_lshrrev_b32_e32 v11, 16, v11
	v_add3_u32 v13, v75, v13, s19
	global_store_dwordx4 v[90:91], v[70:73], off
	ds_read2_b32 v[74:75], v7 offset0:16 offset1:24
	v_lshl_add_u64 v[76:77], v[102:103], 0, v[18:19]
	v_and_or_b32 v70, v13, s20, v11
	v_bfe_u32 v11, v79, 16, 1
	v_add3_u32 v11, v79, v11, s19
	v_bfe_u32 v13, v81, 16, 1
	v_lshrrev_b32_e32 v11, 16, v11
	v_add3_u32 v13, v81, v13, s19
	v_and_or_b32 v71, v13, s20, v11
	v_bfe_u32 v11, v83, 16, 1
	v_add3_u32 v11, v83, v11, s19
	v_bfe_u32 v13, v85, 16, 1
	v_lshrrev_b32_e32 v11, 16, v11
	v_add3_u32 v13, v85, v13, s19
	v_and_or_b32 v72, v13, s20, v11
	v_bfe_u32 v11, v87, 16, 1
	v_add3_u32 v11, v87, v11, s19
	v_bfe_u32 v13, v89, 16, 1
	v_lshrrev_b32_e32 v11, 16, v11
	v_add3_u32 v13, v89, v13, s19
	v_and_or_b32 v73, v13, s20, v11
	global_store_dwordx4 v[76:77], v[70:73], off
	ds_read2_b32 v[76:77], v7 offset0:49 offset1:57
	ds_read2_b32 v[78:79], v7 offset0:82 offset1:90
	ds_read2_b32 v[80:81], v7 offset0:115 offset1:123
	s_waitcnt lgkmcnt(3)
	v_bfe_u32 v11, v74, 16, 1
	v_add3_u32 v11, v74, v11, s19
	s_waitcnt lgkmcnt(2)
	v_bfe_u32 v13, v76, 16, 1
	ds_read2_b32 v[82:83], v7 offset0:148 offset1:156
	v_lshrrev_b32_e32 v11, 16, v11
	v_add3_u32 v13, v76, v13, s19
	ds_read2_b32 v[84:85], v7 offset0:181 offset1:189
	v_and_or_b32 v70, v13, s20, v11
	s_waitcnt lgkmcnt(3)
	v_bfe_u32 v11, v78, 16, 1
	v_add3_u32 v11, v78, v11, s19
	s_waitcnt lgkmcnt(2)
	v_bfe_u32 v13, v80, 16, 1
	ds_read2_b32 v[86:87], v7 offset0:214 offset1:222
	v_lshrrev_b32_e32 v11, 16, v11
	v_add3_u32 v13, v80, v13, s19
	ds_read2_b32 v[88:89], v7 offset0:247 offset1:255
	v_and_or_b32 v71, v13, s20, v11
	s_waitcnt lgkmcnt(3)
	v_bfe_u32 v11, v82, 16, 1
	v_add3_u32 v11, v82, v11, s19
	s_waitcnt lgkmcnt(2)
	v_bfe_u32 v13, v84, 16, 1
	v_lshrrev_b32_e32 v11, 16, v11
	v_add3_u32 v13, v84, v13, s19
	v_and_or_b32 v72, v13, s20, v11
	s_waitcnt lgkmcnt(1)
	v_bfe_u32 v11, v86, 16, 1
	v_add3_u32 v11, v86, v11, s19
	s_waitcnt lgkmcnt(0)
	v_bfe_u32 v13, v88, 16, 1
	v_lshrrev_b32_e32 v11, 16, v11
	v_add3_u32 v13, v88, v13, s19
	v_and_or_b32 v73, v13, s20, v11
	v_bfe_u32 v11, v75, 16, 1
	v_add3_u32 v11, v75, v11, s19
	v_bfe_u32 v13, v77, 16, 1
	v_lshl_add_u64 v[90:91], v[102:103], 0, v[20:21]
	v_lshrrev_b32_e32 v11, 16, v11
	v_add3_u32 v13, v77, v13, s19
	global_store_dwordx4 v[90:91], v[70:73], off
	v_lshl_add_u64 v[74:75], v[102:103], 0, v[22:23]
	s_nop 0
	v_and_or_b32 v70, v13, s20, v11
	v_bfe_u32 v11, v79, 16, 1
	v_add3_u32 v11, v79, v11, s19
	v_bfe_u32 v13, v81, 16, 1
	v_lshrrev_b32_e32 v11, 16, v11
	v_add3_u32 v13, v81, v13, s19
	v_and_or_b32 v71, v13, s20, v11
	v_bfe_u32 v11, v83, 16, 1
	v_add3_u32 v11, v83, v11, s19
	v_bfe_u32 v13, v85, 16, 1
	v_lshrrev_b32_e32 v11, 16, v11
	v_add3_u32 v13, v85, v13, s19
	v_and_or_b32 v72, v13, s20, v11
	v_bfe_u32 v11, v87, 16, 1
	v_add3_u32 v11, v87, v11, s19
	v_bfe_u32 v13, v89, 16, 1
	v_lshrrev_b32_e32 v11, 16, v11
	v_add3_u32 v13, v89, v13, s19
	v_and_or_b32 v73, v13, s20, v11
	global_store_dwordx4 v[74:75], v[70:73], off
	s_waitcnt lgkmcnt(0)
	s_branch .LBB0_154
